# SSD gate loads: one row-address computation per lane, the 4 consecutive rows and 2 column halves reached via offset immediates (replaces 8 separate address chains)
# speedup vs baseline: 1.0073x; 1.0073x over previous
; __device__ __forceinline__ void ssd_item(CPar p, int l, int item, float* sm) {
;     ...
;         bf16_t zq[2][4];
; #pragma unroll
;         for (int c2 = 0; c2 < 2; ++c2)
; #pragma unroll
;             for (int r = 0; r < 4; ++r) { const int t = t0 + rb * 16 + fq * 4 + r; zq[c2][r] = (t < T) ? Z[(size_t)row_of(s, t) * 1024 + h * 64 + chh * 32 + c2 * 16 + fr] : (bf16_t)0; }
.LBB0_439:
	v_add_u32_e32 v83, s11, v124
	v_add_u32_e32 v81, 1, v83
	v_add_u32_e32 v3, 2, v83
	v_add_u32_e32 v1, 3, v83
	v_cmp_gt_i32_e64 s[82:83], s12, v83
	v_cmp_gt_i32_e64 s[80:81], s12, v81
	v_cmp_gt_i32_e64 s[78:79], s12, v3
	v_cmp_gt_i32_e64 s[76:77], s12, v1
	v_mov_b32_e32 v50, 0
	v_mov_b32_e32 v96, 0
	v_mov_b32_e32 v98, 0
	v_mov_b32_e32 v94, 0
	v_mov_b32_e32 v92, 0
	v_mov_b32_e32 v88, 0
	v_mov_b32_e32 v90, 0
	v_mov_b32_e32 v2, 0
	v_mov_b32_e32 v28, s20
	v_mov_b32_e32 v29, s21
	v_cmp_gt_i32_e32 vcc, 16, v83
	s_nop 1
	v_cndmask_b32_e32 v28, v28, v29, vcc
	v_mov_b32_e32 v29, s16
	v_cndmask_b32_e64 v28, v29, v28, s[40:41]
	v_add3_u32 v28, v124, v28, s11
	v_ashrrev_i32_e32 v29, 31, v28
	v_lshlrev_b64 v[28:29], 11, v[28:29]
	v_lshl_add_u64 v[196:197], v[60:61], 0, v[28:29]
	v_mov_b32_e32 v194, 0x1000
	v_mov_b32_e32 v195, 0
	v_lshl_add_u64 v[198:199], v[196:197], 0, v[194:195]
	s_and_saveexec_b64 s[36:37], s[82:83]
	s_cbranch_execz .Lzq_1
	global_load_ushort v50, v[196:197], off
	global_load_ushort v92, v[196:197], off offset:32
.Lzq_1:
	s_or_b64 exec, exec, s[36:37]
	s_and_saveexec_b64 s[36:37], s[80:81]
	s_cbranch_execz .Lzq_2
	global_load_ushort v96, v[196:197], off offset:2048
	global_load_ushort v88, v[196:197], off offset:2080
.Lzq_2:
	s_or_b64 exec, exec, s[36:37]
	s_and_saveexec_b64 s[36:37], s[78:79]
	s_cbranch_execz .Lzq_3
	global_load_ushort v98, v[198:199], off
	global_load_ushort v90, v[198:199], off offset:32
.Lzq_3:
	s_or_b64 exec, exec, s[36:37]
	s_and_saveexec_b64 s[36:37], s[76:77]
	s_cbranch_execz .LBB0_455
	global_load_ushort v94, v[198:199], off offset:2048
	global_load_ushort v2, v[198:199], off offset:2080
